# split barrier also at P3->S1: workgroups >= 64 (w_in tail tiles, independent of P3) arrive without waiting and complete it before the next barrier
# speedup vs baseline: 1.0163x; 1.0016x over previous
.LBB0_697:
	s_mov_b32 s101, -1
	s_getreg_b32 s6, hwreg(HW_REG_XCC_ID, 0, 4)
	s_waitcnt vmcnt(0)
	s_barrier
	s_and_saveexec_b64 s[0:1], s[46:47]
	s_cbranch_execz .LBB0_749
	s_add_i32 s7, 0, 0x20160
	v_mov_b32_e32 v0, s7
	s_waitcnt vmcnt(0) expcnt(0) lgkmcnt(0)
	ds_read_b32 v2, v0
	s_add_i32 s7, 0, 0x20164
	v_mov_b32_e32 v0, s7
	ds_read_b32 v0, v0
	s_and_b32 s60, s6, 15
	s_waitcnt lgkmcnt(1)
	v_cmp_ne_u32_e32 vcc, 0, v2
	s_cbranch_vccnz .LBB0_713
	s_add_u32 s6, s66, 0x1200
	s_addc_u32 s7, s67, 0
	s_add_u32 s10, s66, 0x1400
	s_addc_u32 s11, s67, 0
	s_add_u32 s12, s66, 0x1500
	s_addc_u32 s13, s67, 0
	s_add_u32 s16, s66, 0x1600
	s_addc_u32 s17, s67, 0
	s_add_u32 s18, s66, 0x1700
	s_addc_u32 s19, s67, 0
	s_add_u32 s20, s66, 0x1800
	s_addc_u32 s21, s67, 0
	s_add_u32 s22, s66, 0x1900
	s_addc_u32 s23, s67, 0
	s_add_u32 s24, s66, 0x1a00
	s_addc_u32 s25, s67, 0
	s_add_u32 s26, s66, 0x1b00
	s_addc_u32 s27, s67, 0
	s_add_u32 s28, s66, 0x1c00
	s_addc_u32 s29, s67, 0
	s_add_u32 s30, s66, 0x1d00
	s_addc_u32 s31, s67, 0
	s_add_u32 s34, s66, 0x1e00
	s_addc_u32 s35, s67, 0
	s_add_u32 s36, s66, 0x1f00
	s_addc_u32 s37, s67, 0
	s_add_u32 s38, s66, 0x2000
	s_addc_u32 s39, s67, 0
	s_add_u32 s40, s66, 0x2100
	s_addc_u32 s41, s67, 0
	s_add_u32 s42, s66, 0x2200
	s_addc_u32 s43, s67, 0
	s_mul_i32 s61, s65, s74
	s_add_u32 s44, s66, 0x2300
	s_mul_i32 s61, s61, s64
	s_addc_u32 s45, s67, 0
	s_mov_b32 s62, 1
	v_mov_b32_e32 v16, 0
	s_branch .LBB0_701

.LBB0_715:
	s_or_b64 exec, exec, s[12:13]
	v_cvt_f32_u32_e32 v4, v2
	s_waitcnt vmcnt(0)
	v_readfirstlane_b32 s10, v3
	v_sub_u32_e32 v3, 0, v2
	v_rcp_iflag_f32_e32 v4, v4
	v_add_u32_e32 v5, s10, v1
	v_mul_f32_e32 v4, 0x4f7ffffe, v4
	v_cvt_u32_f32_e32 v4, v4
	v_mul_lo_u32 v1, v3, v4
	v_mul_hi_u32 v1, v4, v1
	v_add_u32_e32 v1, v4, v1
	v_mul_hi_u32 v1, v5, v1
	v_mul_lo_u32 v3, v1, v2
	v_sub_u32_e32 v3, v5, v3
	v_add_u32_e32 v4, 1, v1
	v_cmp_ge_u32_e32 vcc, v3, v2
	s_nop 1
	v_cndmask_b32_e32 v1, v1, v4, vcc
	v_sub_u32_e32 v4, v3, v2
	v_cndmask_b32_e32 v3, v3, v4, vcc
	v_add_u32_e32 v4, 1, v1
	v_cmp_ge_u32_e32 vcc, v3, v2
	v_add_u32_e32 v3, 1, v5
	s_nop 0
	v_cndmask_b32_e32 v1, v1, v4, vcc
	v_mul_lo_u32 v4, v2, v1
	v_add_u32_e32 v2, v4, v2
	v_cmp_ne_u32_e32 vcc, v3, v2
	s_and_saveexec_b64 s[10:11], vcc
	s_xor_b64 s[10:11], exec, s[10:11]
	s_cbranch_execz .LBB0_729
	s_cmp_lt_u32 s2, 64
	s_cbranch_scc1 .Lsb_wait_p0
	s_cmp_lg_u32 s64, 0x100
	s_cbranch_scc1 .Lsb_wait_p0
	v_readfirstlane_b32 s101, v1
	s_branch .LBB0_729

.Lsb_cj_p0:
	s_or_b64 exec, exec, s[0:1]
	s_barrier
	s_mov_b32 s101, -1
	s_getreg_b32 s6, hwreg(HW_REG_XCC_ID, 0, 4)
	s_waitcnt vmcnt(0)
	s_barrier
	s_and_saveexec_b64 s[0:1], s[46:47]
	s_cbranch_execz .LBB0_910
	s_add_i32 s7, 0, 0x20160
	v_mov_b32_e32 v0, s7
	s_waitcnt vmcnt(0) expcnt(0) lgkmcnt(0)
	ds_read_b32 v2, v0
	s_add_i32 s7, 0, 0x20164
	v_mov_b32_e32 v0, s7
	ds_read_b32 v0, v0
	s_and_b32 s62, s6, 15
	s_waitcnt lgkmcnt(1)
	v_cmp_ne_u32_e32 vcc, 0, v2
	s_cbranch_vccnz .LBB0_874
	s_add_u32 s6, s66, 0x1200
	s_addc_u32 s7, s67, 0
	s_add_u32 s10, s66, 0x1400
	s_addc_u32 s11, s67, 0
	s_add_u32 s12, s66, 0x1500
	s_addc_u32 s13, s67, 0
	s_add_u32 s16, s66, 0x1600
	s_addc_u32 s17, s67, 0
	s_add_u32 s18, s66, 0x1700
	s_addc_u32 s19, s67, 0
	s_add_u32 s20, s66, 0x1800
	s_addc_u32 s21, s67, 0
	s_add_u32 s22, s66, 0x1900
	s_addc_u32 s23, s67, 0
	s_add_u32 s24, s66, 0x1a00
	s_addc_u32 s25, s67, 0
	s_add_u32 s26, s66, 0x1b00
	s_addc_u32 s27, s67, 0
	s_add_u32 s28, s66, 0x1c00
	s_addc_u32 s29, s67, 0
	s_add_u32 s30, s66, 0x1d00
	s_addc_u32 s31, s67, 0
	s_add_u32 s34, s66, 0x1e00
	s_addc_u32 s35, s67, 0
	s_add_u32 s36, s66, 0x1f00
	s_addc_u32 s37, s67, 0
	s_add_u32 s38, s66, 0x2000
	s_addc_u32 s39, s67, 0
	s_add_u32 s40, s66, 0x2100
	s_addc_u32 s41, s67, 0
	s_add_u32 s42, s66, 0x2200
	s_addc_u32 s43, s67, 0
	s_mul_i32 s63, s65, s74
	s_add_u32 s44, s66, 0x2300
	s_mul_i32 s63, s63, s64
	s_addc_u32 s45, s67, 0
	s_mov_b32 s70, 1
	v_mov_b32_e32 v16, 0
	s_branch .LBB0_862

.LBB0_876:
	s_or_b64 exec, exec, s[12:13]
	v_cvt_f32_u32_e32 v4, v2
	s_waitcnt vmcnt(0)
	v_readfirstlane_b32 s10, v3
	v_sub_u32_e32 v3, 0, v2
	v_rcp_iflag_f32_e32 v4, v4
	v_add_u32_e32 v5, s10, v1
	v_mul_f32_e32 v4, 0x4f7ffffe, v4
	v_cvt_u32_f32_e32 v4, v4
	v_mul_lo_u32 v1, v3, v4
	v_mul_hi_u32 v1, v4, v1
	v_add_u32_e32 v1, v4, v1
	v_mul_hi_u32 v1, v5, v1
	v_mul_lo_u32 v3, v1, v2
	v_sub_u32_e32 v3, v5, v3
	v_add_u32_e32 v4, 1, v1
	v_cmp_ge_u32_e32 vcc, v3, v2
	s_nop 1
	v_cndmask_b32_e32 v1, v1, v4, vcc
	v_sub_u32_e32 v4, v3, v2
	v_cndmask_b32_e32 v3, v3, v4, vcc
	v_add_u32_e32 v4, 1, v1
	v_cmp_ge_u32_e32 vcc, v3, v2
	v_add_u32_e32 v3, 1, v5
	s_nop 0
	v_cndmask_b32_e32 v1, v1, v4, vcc
	v_mul_lo_u32 v4, v2, v1
	v_add_u32_e32 v2, v4, v2
	v_cmp_ne_u32_e32 vcc, v3, v2
	s_and_saveexec_b64 s[10:11], vcc
	s_xor_b64 s[10:11], exec, s[10:11]
	s_cbranch_execz .LBB0_890
	s_cmp_lt_u32 s2, 128
	s_cbranch_scc1 .Lsb_wait_a0
	s_cmp_lg_u32 s64, 0x100
	s_cbranch_scc1 .Lsb_wait_a0
	v_readfirstlane_b32 s101, v1
	s_branch .LBB0_890

.LBB0_972:
	s_or_b64 exec, exec, s[16:17]
	v_cvt_f32_u32_e32 v4, v2
	s_waitcnt vmcnt(0)
	v_readfirstlane_b32 s10, v3
	v_sub_u32_e32 v3, 0, v2
	v_rcp_iflag_f32_e32 v4, v4
	v_add_u32_e32 v5, s10, v1
	v_mul_f32_e32 v4, 0x4f7ffffe, v4
	v_cvt_u32_f32_e32 v4, v4
	v_mul_lo_u32 v1, v3, v4
	v_mul_hi_u32 v1, v4, v1
	v_add_u32_e32 v1, v4, v1
	v_mul_hi_u32 v1, v5, v1
	v_mul_lo_u32 v3, v1, v2
	v_sub_u32_e32 v3, v5, v3
	v_add_u32_e32 v4, 1, v1
	v_cmp_ge_u32_e32 vcc, v3, v2
	s_nop 1
	v_cndmask_b32_e32 v1, v1, v4, vcc
	v_sub_u32_e32 v4, v3, v2
	v_cndmask_b32_e32 v3, v3, v4, vcc
	v_add_u32_e32 v4, 1, v1
	v_cmp_ge_u32_e32 vcc, v3, v2
	v_add_u32_e32 v3, 1, v5
	s_nop 0
	v_cndmask_b32_e32 v1, v1, v4, vcc
	v_mul_lo_u32 v4, v2, v1
	v_add_u32_e32 v2, v4, v2
	v_cmp_ne_u32_e32 vcc, v3, v2
	s_and_saveexec_b64 s[10:11], vcc
	s_xor_b64 s[10:11], exec, s[10:11]
	s_cbranch_execz .LBB0_986
	s_cmp_lt_u32 s2, 128
	s_cbranch_scc1 .Lsb_wait_b0
	s_cmp_lg_u32 s64, 0x100
	s_cbranch_scc1 .Lsb_wait_b0
	v_readfirstlane_b32 s101, v1
	s_branch .LBB0_986

.LBB0_2307:
	s_mov_b32 s101, -1
	s_getreg_b32 s8, hwreg(HW_REG_XCC_ID, 0, 4)
	s_waitcnt vmcnt(0)
	s_barrier
	s_and_saveexec_b64 s[0:1], s[46:47]
	s_cbranch_execz .LBB0_2359
	s_add_i32 s9, 0, 0x20160
	v_mov_b32_e32 v0, s9
	s_waitcnt vmcnt(0) expcnt(0) lgkmcnt(0)
	ds_read_b32 v2, v0
	s_add_i32 s9, 0, 0x20164
	v_mov_b32_e32 v0, s9
	ds_read_b32 v0, v0
	s_and_b32 s51, s8, 15
	s_waitcnt lgkmcnt(1)
	v_cmp_ne_u32_e32 vcc, 0, v2
	s_cbranch_vccnz .LBB0_2323
	s_add_u32 s8, s66, 0x1200
	s_addc_u32 s9, s67, 0
	s_add_u32 s14, s66, 0x1400
	s_addc_u32 s15, s67, 0
	s_add_u32 s16, s66, 0x1500
	s_addc_u32 s17, s67, 0
	s_add_u32 s18, s66, 0x1600
	s_addc_u32 s19, s67, 0
	s_add_u32 s20, s66, 0x1700
	s_addc_u32 s21, s67, 0
	s_add_u32 s22, s66, 0x1800
	s_addc_u32 s23, s67, 0
	s_add_u32 s24, s66, 0x1900
	s_addc_u32 s25, s67, 0
	s_add_u32 s26, s66, 0x1a00
	s_addc_u32 s27, s67, 0
	s_add_u32 s28, s66, 0x1b00
	s_addc_u32 s29, s67, 0
	s_add_u32 s30, s66, 0x1c00
	s_addc_u32 s31, s67, 0
	s_add_u32 s34, s66, 0x1d00
	s_addc_u32 s35, s67, 0
	s_add_u32 s36, s66, 0x1e00
	s_addc_u32 s37, s67, 0
	s_add_u32 s38, s66, 0x1f00
	s_addc_u32 s39, s67, 0
	s_add_u32 s40, s66, 0x2000
	s_addc_u32 s41, s67, 0
	s_add_u32 s42, s66, 0x2100
	s_addc_u32 s43, s67, 0
	s_add_u32 s44, s66, 0x2200
	s_addc_u32 s45, s67, 0
	s_mul_i32 s62, s65, s74
	s_add_u32 s52, s66, 0x2300
	s_mul_i32 s62, s62, s64
	s_addc_u32 s53, s67, 0
	s_mov_b32 s63, 1
	v_mov_b32_e32 v16, 0
	s_branch .LBB0_2311

.LBB0_2325:
	s_or_b64 exec, exec, s[16:17]
	v_cvt_f32_u32_e32 v4, v2
	s_waitcnt vmcnt(0)
	v_readfirstlane_b32 s14, v3
	v_sub_u32_e32 v3, 0, v2
	v_rcp_iflag_f32_e32 v4, v4
	v_add_u32_e32 v5, s14, v1
	v_mul_f32_e32 v4, 0x4f7ffffe, v4
	v_cvt_u32_f32_e32 v4, v4
	v_mul_lo_u32 v1, v3, v4
	v_mul_hi_u32 v1, v4, v1
	v_add_u32_e32 v1, v4, v1
	v_mul_hi_u32 v1, v5, v1
	v_mul_lo_u32 v3, v1, v2
	v_sub_u32_e32 v3, v5, v3
	v_add_u32_e32 v4, 1, v1
	v_cmp_ge_u32_e32 vcc, v3, v2
	s_nop 1
	v_cndmask_b32_e32 v1, v1, v4, vcc
	v_sub_u32_e32 v4, v3, v2
	v_cndmask_b32_e32 v3, v3, v4, vcc
	v_add_u32_e32 v4, 1, v1
	v_cmp_ge_u32_e32 vcc, v3, v2
	v_add_u32_e32 v3, 1, v5
	s_nop 0
	v_cndmask_b32_e32 v1, v1, v4, vcc
	v_mul_lo_u32 v4, v2, v1
	v_add_u32_e32 v2, v4, v2
	v_cmp_ne_u32_e32 vcc, v3, v2
	s_and_saveexec_b64 s[14:15], vcc
	s_xor_b64 s[14:15], exec, s[14:15]
	s_cbranch_execz .LBB0_2339
	s_cmp_lt_u32 s2, 64
	s_cbranch_scc1 .Lsb_wait_p1
	s_cmp_lg_u32 s64, 0x100
	s_cbranch_scc1 .Lsb_wait_p1
	v_readfirstlane_b32 s101, v1
	s_branch .LBB0_2339

.Lsb_cj_p1:
	s_or_b64 exec, exec, s[0:1]
	s_barrier
	s_mov_b32 s101, -1
	s_getreg_b32 s8, hwreg(HW_REG_XCC_ID, 0, 4)
	s_waitcnt vmcnt(0)
	s_barrier
	s_and_saveexec_b64 s[0:1], s[46:47]
	s_cbranch_execz .LBB0_2520
	s_add_i32 s9, 0, 0x20160
	v_mov_b32_e32 v0, s9
	s_waitcnt vmcnt(0) expcnt(0) lgkmcnt(0)
	ds_read_b32 v2, v0
	s_add_i32 s9, 0, 0x20164
	v_mov_b32_e32 v0, s9
	ds_read_b32 v0, v0
	s_and_b32 s51, s8, 15
	s_waitcnt lgkmcnt(1)
	v_cmp_ne_u32_e32 vcc, 0, v2
	s_cbranch_vccnz .LBB0_2484
	s_add_u32 s8, s66, 0x1200
	s_addc_u32 s9, s67, 0
	s_add_u32 s14, s66, 0x1400
	s_addc_u32 s15, s67, 0
	s_add_u32 s16, s66, 0x1500
	s_addc_u32 s17, s67, 0
	s_add_u32 s18, s66, 0x1600
	s_addc_u32 s19, s67, 0
	s_add_u32 s20, s66, 0x1700
	s_addc_u32 s21, s67, 0
	s_add_u32 s22, s66, 0x1800
	s_addc_u32 s23, s67, 0
	s_add_u32 s24, s66, 0x1900
	s_addc_u32 s25, s67, 0
	s_add_u32 s26, s66, 0x1a00
	s_addc_u32 s27, s67, 0
	s_add_u32 s28, s66, 0x1b00
	s_addc_u32 s29, s67, 0
	s_add_u32 s30, s66, 0x1c00
	s_addc_u32 s31, s67, 0
	s_add_u32 s34, s66, 0x1d00
	s_addc_u32 s35, s67, 0
	s_add_u32 s36, s66, 0x1e00
	s_addc_u32 s37, s67, 0
	s_add_u32 s38, s66, 0x1f00
	s_addc_u32 s39, s67, 0
	s_add_u32 s40, s66, 0x2000
	s_addc_u32 s41, s67, 0
	s_add_u32 s42, s66, 0x2100
	s_addc_u32 s43, s67, 0
	s_add_u32 s44, s66, 0x2200
	s_addc_u32 s45, s67, 0
	s_mul_i32 s58, s65, s74
	s_add_u32 s48, s66, 0x2300
	s_mul_i32 s58, s58, s64
	s_addc_u32 s49, s67, 0
	s_mov_b32 s59, 1
	v_mov_b32_e32 v16, 0
	s_branch .LBB0_2472

.LBB0_2486:
	s_or_b64 exec, exec, s[16:17]
	v_cvt_f32_u32_e32 v4, v2
	s_waitcnt vmcnt(0)
	v_readfirstlane_b32 s14, v3
	v_sub_u32_e32 v3, 0, v2
	v_rcp_iflag_f32_e32 v4, v4
	v_add_u32_e32 v5, s14, v1
	v_mul_f32_e32 v4, 0x4f7ffffe, v4
	v_cvt_u32_f32_e32 v4, v4
	v_mul_lo_u32 v1, v3, v4
	v_mul_hi_u32 v1, v4, v1
	v_add_u32_e32 v1, v4, v1
	v_mul_hi_u32 v1, v5, v1
	v_mul_lo_u32 v3, v1, v2
	v_sub_u32_e32 v3, v5, v3
	v_add_u32_e32 v4, 1, v1
	v_cmp_ge_u32_e32 vcc, v3, v2
	s_nop 1
	v_cndmask_b32_e32 v1, v1, v4, vcc
	v_sub_u32_e32 v4, v3, v2
	v_cndmask_b32_e32 v3, v3, v4, vcc
	v_add_u32_e32 v4, 1, v1
	v_cmp_ge_u32_e32 vcc, v3, v2
	v_add_u32_e32 v3, 1, v5
	s_nop 0
	v_cndmask_b32_e32 v1, v1, v4, vcc
	v_mul_lo_u32 v4, v2, v1
	v_add_u32_e32 v2, v4, v2
	v_cmp_ne_u32_e32 vcc, v3, v2
	s_and_saveexec_b64 s[14:15], vcc
	s_xor_b64 s[14:15], exec, s[14:15]
	s_cbranch_execz .LBB0_2500
	s_cmp_lt_u32 s2, 128
	s_cbranch_scc1 .Lsb_wait_a1
	s_cmp_lg_u32 s64, 0x100
	s_cbranch_scc1 .Lsb_wait_a1
	v_readfirstlane_b32 s101, v1
	s_branch .LBB0_2500
